# P5 and P6' K-loop heads aligned to a 64-byte instruction line (.p2align 6 in the preheader), on top of v071
# baseline (speedup 1.0000x reference)
.LBB0_506:
	s_add_u32 s42, s42, 0x80080
	s_addc_u32 s43, s43, 0
	s_add_u32 s17, s44, 0x100
	v_mov_b32_e32 v0, 0
	s_addc_u32 s21, s45, 0
	s_mov_b32 s52, -2
	v_mov_b32_e32 v1, v0
	v_mov_b32_e32 v2, v0
	v_mov_b32_e32 v3, v0
	v_mov_b32_e32 v4, v0
	v_mov_b32_e32 v5, v0
	v_mov_b32_e32 v6, v0
	v_mov_b32_e32 v7, v0
	v_mov_b32_e32 v16, v0
	v_mov_b32_e32 v17, v0
	v_mov_b32_e32 v18, v0
	v_mov_b32_e32 v19, v0
	v_mov_b32_e32 v20, v0
	v_mov_b32_e32 v21, v0
	v_mov_b32_e32 v22, v0
	v_mov_b32_e32 v23, v0
	v_mov_b32_e32 v32, v0
	v_mov_b32_e32 v33, v0
	v_mov_b32_e32 v34, v0
	v_mov_b32_e32 v35, v0
	v_mov_b32_e32 v36, v0
	v_mov_b32_e32 v37, v0
	v_mov_b32_e32 v38, v0
	v_mov_b32_e32 v39, v0
	v_mov_b32_e32 v48, v0
	v_mov_b32_e32 v49, v0
	v_mov_b32_e32 v50, v0
	v_mov_b32_e32 v51, v0
	v_mov_b32_e32 v52, v0
	v_mov_b32_e32 v53, v0
	v_mov_b32_e32 v54, v0
	v_mov_b32_e32 v55, v0
	v_mov_b32_e32 v8, v0
	v_mov_b32_e32 v9, v0
	v_mov_b32_e32 v10, v0
	v_mov_b32_e32 v11, v0
	v_mov_b32_e32 v12, v0
	v_mov_b32_e32 v13, v0
	v_mov_b32_e32 v14, v0
	v_mov_b32_e32 v15, v0
	v_mov_b32_e32 v24, v0
	v_mov_b32_e32 v25, v0
	v_mov_b32_e32 v26, v0
	v_mov_b32_e32 v27, v0
	v_mov_b32_e32 v28, v0
	v_mov_b32_e32 v29, v0
	v_mov_b32_e32 v30, v0
	v_mov_b32_e32 v31, v0
	v_mov_b32_e32 v40, v0
	v_mov_b32_e32 v41, v0
	v_mov_b32_e32 v42, v0
	v_mov_b32_e32 v43, v0
	v_mov_b32_e32 v44, v0
	v_mov_b32_e32 v45, v0
	v_mov_b32_e32 v46, v0
	v_mov_b32_e32 v47, v0
	v_mov_b32_e32 v56, v0
	v_mov_b32_e32 v57, v0
	v_mov_b32_e32 v58, v0
	v_mov_b32_e32 v59, v0
	v_mov_b32_e32 v60, v0
	v_mov_b32_e32 v61, v0
	v_mov_b32_e32 v62, v0
	v_mov_b32_e32 v63, v0
	v_mov_b32_e32 v64, v0
	v_mov_b32_e32 v65, v0
	v_mov_b32_e32 v66, v0
	v_mov_b32_e32 v67, v0
	v_mov_b32_e32 v68, v0
	v_mov_b32_e32 v69, v0
	v_mov_b32_e32 v70, v0
	v_mov_b32_e32 v71, v0
	v_mov_b32_e32 v80, v0
	v_mov_b32_e32 v81, v0
	v_mov_b32_e32 v82, v0
	v_mov_b32_e32 v83, v0
	v_mov_b32_e32 v84, v0
	v_mov_b32_e32 v85, v0
	v_mov_b32_e32 v86, v0
	v_mov_b32_e32 v87, v0
	v_mov_b32_e32 v96, v0
	v_mov_b32_e32 v97, v0
	v_mov_b32_e32 v98, v0
	v_mov_b32_e32 v99, v0
	v_mov_b32_e32 v100, v0
	v_mov_b32_e32 v101, v0
	v_mov_b32_e32 v102, v0
	v_mov_b32_e32 v103, v0
	v_mov_b32_e32 v112, v0
	v_mov_b32_e32 v113, v0
	v_mov_b32_e32 v114, v0
	v_mov_b32_e32 v115, v0
	v_mov_b32_e32 v116, v0
	v_mov_b32_e32 v117, v0
	v_mov_b32_e32 v118, v0
	v_mov_b32_e32 v119, v0
	v_mov_b32_e32 v72, v0
	v_mov_b32_e32 v73, v0
	v_mov_b32_e32 v74, v0
	v_mov_b32_e32 v75, v0
	v_mov_b32_e32 v76, v0
	v_mov_b32_e32 v77, v0
	v_mov_b32_e32 v78, v0
	v_mov_b32_e32 v79, v0
	v_mov_b32_e32 v88, v0
	v_mov_b32_e32 v89, v0
	v_mov_b32_e32 v90, v0
	v_mov_b32_e32 v91, v0
	v_mov_b32_e32 v92, v0
	v_mov_b32_e32 v93, v0
	v_mov_b32_e32 v94, v0
	v_mov_b32_e32 v95, v0
	v_mov_b32_e32 v104, v0
	v_mov_b32_e32 v105, v0
	v_mov_b32_e32 v106, v0
	v_mov_b32_e32 v107, v0
	v_mov_b32_e32 v108, v0
	v_mov_b32_e32 v109, v0
	v_mov_b32_e32 v110, v0
	v_mov_b32_e32 v111, v0
	v_mov_b32_e32 v120, v0
	v_mov_b32_e32 v121, v0
	v_mov_b32_e32 v122, v0
	v_mov_b32_e32 v123, v0
	v_mov_b32_e32 v124, v0
	v_mov_b32_e32 v125, v0
	v_mov_b32_e32 v126, v0
	v_mov_b32_e32 v127, v0
	.p2align 6
	v_readlane_b32 s54, v254, 6
	s_nop 3
	s_cmp_ge_u32 s54, 0x100
	s_cbranch_scc0 .Lsprio_p5
	s_setprio 1

.LBB0_673:
	s_and_b64 s[30:31], s[22:23], exec
	s_cselect_b32 s3, s11, s25
	s_cselect_b32 s29, s10, s24
	s_add_u32 s24, s24, 0xc000
	v_mov_b32_e32 v0, 0
	s_addc_u32 s25, s25, 0
	s_mov_b32 s45, -2
	s_mov_b64 s[30:31], s[20:21]
	v_mov_b32_e32 v1, v0
	v_mov_b32_e32 v2, v0
	v_mov_b32_e32 v3, v0
	v_mov_b32_e32 v4, v0
	v_mov_b32_e32 v5, v0
	v_mov_b32_e32 v6, v0
	v_mov_b32_e32 v7, v0
	v_mov_b32_e32 v16, v0
	v_mov_b32_e32 v17, v0
	v_mov_b32_e32 v18, v0
	v_mov_b32_e32 v19, v0
	v_mov_b32_e32 v20, v0
	v_mov_b32_e32 v21, v0
	v_mov_b32_e32 v22, v0
	v_mov_b32_e32 v23, v0
	v_mov_b32_e32 v32, v0
	v_mov_b32_e32 v33, v0
	v_mov_b32_e32 v34, v0
	v_mov_b32_e32 v35, v0
	v_mov_b32_e32 v36, v0
	v_mov_b32_e32 v37, v0
	v_mov_b32_e32 v38, v0
	v_mov_b32_e32 v39, v0
	v_mov_b32_e32 v48, v0
	v_mov_b32_e32 v49, v0
	v_mov_b32_e32 v50, v0
	v_mov_b32_e32 v51, v0
	v_mov_b32_e32 v52, v0
	v_mov_b32_e32 v53, v0
	v_mov_b32_e32 v54, v0
	v_mov_b32_e32 v55, v0
	v_mov_b32_e32 v8, v0
	v_mov_b32_e32 v9, v0
	v_mov_b32_e32 v10, v0
	v_mov_b32_e32 v11, v0
	v_mov_b32_e32 v12, v0
	v_mov_b32_e32 v13, v0
	v_mov_b32_e32 v14, v0
	v_mov_b32_e32 v15, v0
	v_mov_b32_e32 v24, v0
	v_mov_b32_e32 v25, v0
	v_mov_b32_e32 v26, v0
	v_mov_b32_e32 v27, v0
	v_mov_b32_e32 v28, v0
	v_mov_b32_e32 v29, v0
	v_mov_b32_e32 v30, v0
	v_mov_b32_e32 v31, v0
	v_mov_b32_e32 v40, v0
	v_mov_b32_e32 v41, v0
	v_mov_b32_e32 v42, v0
	v_mov_b32_e32 v43, v0
	v_mov_b32_e32 v44, v0
	v_mov_b32_e32 v45, v0
	v_mov_b32_e32 v46, v0
	v_mov_b32_e32 v47, v0
	v_mov_b32_e32 v56, v0
	v_mov_b32_e32 v57, v0
	v_mov_b32_e32 v58, v0
	v_mov_b32_e32 v59, v0
	v_mov_b32_e32 v60, v0
	v_mov_b32_e32 v61, v0
	v_mov_b32_e32 v62, v0
	v_mov_b32_e32 v63, v0
	v_mov_b32_e32 v64, v0
	v_mov_b32_e32 v65, v0
	v_mov_b32_e32 v66, v0
	v_mov_b32_e32 v67, v0
	v_mov_b32_e32 v68, v0
	v_mov_b32_e32 v69, v0
	v_mov_b32_e32 v70, v0
	v_mov_b32_e32 v71, v0
	v_mov_b32_e32 v80, v0
	v_mov_b32_e32 v81, v0
	v_mov_b32_e32 v82, v0
	v_mov_b32_e32 v83, v0
	v_mov_b32_e32 v84, v0
	v_mov_b32_e32 v85, v0
	v_mov_b32_e32 v86, v0
	v_mov_b32_e32 v87, v0
	v_mov_b32_e32 v96, v0
	v_mov_b32_e32 v97, v0
	v_mov_b32_e32 v98, v0
	v_mov_b32_e32 v99, v0
	v_mov_b32_e32 v100, v0
	v_mov_b32_e32 v101, v0
	v_mov_b32_e32 v102, v0
	v_mov_b32_e32 v103, v0
	v_mov_b32_e32 v112, v0
	v_mov_b32_e32 v113, v0
	v_mov_b32_e32 v114, v0
	v_mov_b32_e32 v115, v0
	v_mov_b32_e32 v116, v0
	v_mov_b32_e32 v117, v0
	v_mov_b32_e32 v118, v0
	v_mov_b32_e32 v119, v0
	v_mov_b32_e32 v72, v0
	v_mov_b32_e32 v73, v0
	v_mov_b32_e32 v74, v0
	v_mov_b32_e32 v75, v0
	v_mov_b32_e32 v76, v0
	v_mov_b32_e32 v77, v0
	v_mov_b32_e32 v78, v0
	v_mov_b32_e32 v79, v0
	v_mov_b32_e32 v88, v0
	v_mov_b32_e32 v89, v0
	v_mov_b32_e32 v90, v0
	v_mov_b32_e32 v91, v0
	v_mov_b32_e32 v92, v0
	v_mov_b32_e32 v93, v0
	v_mov_b32_e32 v94, v0
	v_mov_b32_e32 v95, v0
	v_mov_b32_e32 v104, v0
	v_mov_b32_e32 v105, v0
	v_mov_b32_e32 v106, v0
	v_mov_b32_e32 v107, v0
	v_mov_b32_e32 v108, v0
	v_mov_b32_e32 v109, v0
	v_mov_b32_e32 v110, v0
	v_mov_b32_e32 v111, v0
	v_mov_b32_e32 v120, v0
	v_mov_b32_e32 v121, v0
	v_mov_b32_e32 v122, v0
	v_mov_b32_e32 v123, v0
	v_mov_b32_e32 v124, v0
	v_mov_b32_e32 v125, v0
	v_mov_b32_e32 v126, v0
	v_mov_b32_e32 v127, v0
	.p2align 6
	v_readlane_b32 s36, v254, 6
	s_nop 3
	s_cmp_ge_u32 s36, 0x100
	s_cbranch_scc0 .Lsprio_p6
	s_setprio 1
